# P3 loop: QK MFMAs reordered p0 chain first, p0 bias-add+exp executed in the p1 chain's MFMA shadows, PV segment VALU regenerated
# speedup vs baseline: 1.0445x; 1.0058x over previous
.LBB0_323:
	s_add_i32 s0, s79, 0xffff0000
	s_and_b32 s0, s0, 0x18000
	v_add_u32_e32 v84, s0, v238
	v_add_u32_e32 v85, v84, v230
	v_add_u32_e32 v254, v84, v231
	v_add_u32_e32 v255, v84, v232
	v_add_u32_e32 v84, v84, v233
	ds_read_b128 v[80:83], v85 offset:16384
	ds_read_b128 v[202:205], v254 offset:16384
	ds_read_b128 v[194:197], v255 offset:16384
	ds_read_b128 v[186:189], v84 offset:16384
	ds_read_b128 v[198:201], v85 offset:20480
	ds_read_b128 v[190:193], v254 offset:20480
	ds_read_b128 v[246:249], v255 offset:20480
	ds_read_b128 v[250:253], v84 offset:20480
	s_add_i32 s0, s79, 0xfffe8000
	s_and_b32 s0, s0, 0x18000
	s_add_i32 s3, s0, 0
	v_add_u32_e32 v158, s3, v235
	ds_read_b64_tr_b16 v[182:183], v158 offset:32768
	ds_read_b64_tr_b16 v[184:185], v158 offset:34816
	ds_read_b64_tr_b16 v[178:179], v158 offset:36864
	ds_read_b64_tr_b16 v[180:181], v158 offset:38912
	s_add_i32 s0, s72, 3
	s_cmp_ge_i32 s0, s33
	s_cbranch_scc1 .LBB0_325
	s_and_b32 s0, s79, 0x18000
	s_add_i32 m0, s0, s94
	s_add_i32 s1, s90, s0
	global_load_lds_dwordx4 v[220:221], off
	s_mov_b32 m0, s1
	s_add_i32 s1, s0, s66
	global_load_lds_dwordx4 v[218:219], off
	s_mov_b32 m0, s1
	s_add_i32 s0, s0, s67
	global_load_lds_dwordx4 v[224:225], off
	s_mov_b32 m0, s0
	s_nop 0
	global_load_lds_dwordx4 v[222:223], off
	v_lshl_add_u64 v[218:219], v[218:219], 0, s[88:89]
	v_lshl_add_u64 v[220:221], v[220:221], 0, s[88:89]
	v_lshl_add_u64 v[222:223], v[222:223], 0, s[92:93]
	v_lshl_add_u64 v[224:225], v[224:225], 0, s[92:93]
.LBB0_325:
	s_waitcnt lgkmcnt(11)
	v_mfma_f32_32x32x16_bf16 v[96:111], v[80:83], v[144:147], v[64:79]
	v_mov_b32_e32 v170, v148
	s_add_i32 s0, s74, s97
	s_sub_i32 s0, s0, 63
	s_waitcnt lgkmcnt(10)
	v_mfma_f32_32x32x16_bf16 v[96:111], v[202:205], v[140:143], v[96:111]
	v_cvt_f32_i32_e32 v148, s0
	v_mov_b32_e32 v174, v152
	v_mov_b32_e32 v175, v153
	s_waitcnt lgkmcnt(9)
	v_mfma_f32_32x32x16_bf16 v[96:111], v[194:197], v[136:139], v[96:111]
	v_fma_f32 v254, v208, v148, -v207
	v_mov_b32_e32 v176, v154
	v_mov_b32_e32 v177, v155
	s_waitcnt lgkmcnt(8)
	v_mfma_f32_32x32x16_bf16 v[96:111], v[186:189], v[132:135], v[96:111]
	v_add_f32_e32 v255, v237, v254
	v_mov_b32_e32 v168, v162
	v_mov_b32_e32 v162, v156
	s_waitcnt lgkmcnt(7)
	v_mfma_f32_32x32x16_bf16 v[80:95], v[198:201], v[144:147], v[64:79]
	v_mov_b32_e32 v163, v157
	v_mov_b32_e32 v166, v160
	v_mov_b32_e32 v167, v161
	v_mov_b32_e32 v171, v149
	v_mov_b32_e32 v172, v150
	v_mov_b32_e32 v173, v151
	s_waitcnt lgkmcnt(6)
	v_mfma_f32_32x32x16_bf16 v[80:95], v[190:193], v[140:143], v[80:95]
	v_add_f32_e32 v96, v254, v96
	v_exp_f32_e32 v96, v96
	v_add_f32_e32 v97, v254, v97
	v_exp_f32_e32 v97, v97
	v_add_f32_e32 v98, v254, v98
	v_exp_f32_e32 v98, v98
	v_add_f32_e32 v99, v254, v99
	v_exp_f32_e32 v99, v99
	v_add_f32_e32 v100, v254, v100
	v_exp_f32_e32 v100, v100
	s_waitcnt lgkmcnt(5)
	v_mfma_f32_32x32x16_bf16 v[80:95], v[246:249], v[136:139], v[80:95]
	v_add_f32_e32 v101, v254, v101
	v_exp_f32_e32 v101, v101
	v_add_f32_e32 v102, v254, v102
	v_exp_f32_e32 v102, v102
	v_add_f32_e32 v103, v254, v103
	v_exp_f32_e32 v103, v103
	v_add_f32_e32 v104, v254, v104
	v_exp_f32_e32 v104, v104
	v_add_f32_e32 v105, v254, v105
	v_exp_f32_e32 v105, v105
	s_waitcnt lgkmcnt(4)
	v_mfma_f32_32x32x16_bf16 v[80:95], v[250:253], v[132:135], v[80:95]
	v_add_f32_e32 v106, v254, v106
	v_exp_f32_e32 v106, v106
	v_add_f32_e32 v107, v254, v107
	v_exp_f32_e32 v107, v107
	v_add_f32_e32 v108, v254, v108
	v_exp_f32_e32 v108, v108
	v_add_f32_e32 v109, v254, v109
	v_exp_f32_e32 v109, v109
	v_add_f32_e32 v110, v254, v110
	v_exp_f32_e32 v110, v110
	v_add_f32_e32 v111, v254, v111
	v_exp_f32_e32 v111, v111
	s_cmp_le_i32 s97, s78
	s_cbranch_scc1 .LBB0_327
	v_cmp_gt_i32_e64 s[60:61], 26, v240
	v_cmp_gt_i32_e64 s[62:63], 27, v240
	v_cmp_gt_i32_e64 s[58:59], 25, v240
	s_and_b64 s[60:61], s[62:63], s[60:61]
	v_cmp_gt_i32_e64 s[56:57], 24, v240
	s_and_b64 s[58:59], s[60:61], s[58:59]
	v_cmp_gt_i32_e64 s[54:55], 19, v240
	s_and_b64 s[56:57], s[58:59], s[56:57]
	v_cmp_gt_i32_e64 s[52:53], 18, v240
	s_and_b64 s[54:55], s[56:57], s[54:55]
	v_cmp_gt_i32_e64 s[50:51], 17, v240
	s_and_b64 s[52:53], s[54:55], s[52:53]
	v_cmp_gt_i32_e64 s[48:49], 16, v240
	s_and_b64 s[50:51], s[52:53], s[50:51]
	v_cmp_gt_i32_e64 s[46:47], 11, v240
	s_and_b64 s[48:49], s[50:51], s[48:49]
	v_cmp_gt_i32_e64 s[44:45], 10, v240
	s_and_b64 s[46:47], s[48:49], s[46:47]
	v_cmp_gt_i32_e64 s[42:43], 9, v240
	s_and_b64 s[44:45], s[46:47], s[44:45]
	v_cmp_gt_i32_e64 s[40:41], 8, v240
	s_and_b64 s[42:43], s[44:45], s[42:43]
	v_cmp_gt_i32_e64 s[38:39], 3, v240
	s_and_b64 s[40:41], s[42:43], s[40:41]
	v_cmp_gt_i32_e64 s[36:37], 2, v240
	s_and_b64 s[38:39], s[40:41], s[38:39]
	v_cmp_gt_i32_e64 s[34:35], 1, v240
	s_and_b64 s[36:37], s[38:39], s[36:37]
	v_cmp_gt_i32_e64 s[30:31], 0, v240
	s_and_b64 s[34:35], s[36:37], s[34:35]
	s_and_b64 s[30:31], s[34:35], s[30:31]
	v_cmp_gt_i32_e64 s[28:29], 58, v240
	v_cndmask_b32_e64 v96, v96, v113, s[30:31]
	v_cmp_gt_i32_e64 s[30:31], 59, v240
	v_cmp_gt_i32_e64 s[26:27], 57, v240
	s_and_b64 s[28:29], s[30:31], s[28:29]
	v_cmp_gt_i32_e64 s[24:25], 56, v240
	s_and_b64 s[26:27], s[28:29], s[26:27]
	v_cmp_gt_i32_e64 s[22:23], 51, v240
	s_and_b64 s[24:25], s[26:27], s[24:25]
	v_cmp_gt_i32_e64 s[20:21], 50, v240
	s_and_b64 s[22:23], s[24:25], s[22:23]
	v_cmp_gt_i32_e64 s[18:19], 49, v240
	s_and_b64 s[20:21], s[22:23], s[20:21]
	v_cmp_gt_i32_e64 s[16:17], 48, v240
	s_and_b64 s[18:19], s[20:21], s[18:19]
	v_cmp_gt_i32_e64 s[14:15], 43, v240
	s_and_b64 s[16:17], s[18:19], s[16:17]
	v_cmp_gt_i32_e64 s[12:13], 42, v240
	s_and_b64 s[14:15], s[16:17], s[14:15]
	v_cmp_gt_i32_e64 s[10:11], 41, v240
	s_and_b64 s[12:13], s[14:15], s[12:13]
	v_cmp_gt_i32_e64 s[8:9], 40, v240
	s_and_b64 s[10:11], s[12:13], s[10:11]
	v_cmp_gt_i32_e64 s[6:7], 35, v240
	s_and_b64 s[8:9], s[10:11], s[8:9]
	v_cmp_gt_i32_e64 s[4:5], 34, v240
	s_and_b64 s[6:7], s[8:9], s[6:7]
	v_cmp_gt_i32_e64 s[0:1], 33, v240
	s_and_b64 s[4:5], s[6:7], s[4:5]
	v_cmp_gt_i32_e32 vcc, 32, v240
	s_and_b64 s[0:1], s[4:5], s[0:1]
	s_and_b64 vcc, s[0:1], vcc
	v_cndmask_b32_e64 v111, v111, v113, s[62:63]
	v_cndmask_b32_e64 v110, v110, v113, s[60:61]
	v_cndmask_b32_e64 v109, v109, v113, s[58:59]
	v_cndmask_b32_e64 v108, v108, v113, s[56:57]
	v_cndmask_b32_e64 v107, v107, v113, s[54:55]
	v_cndmask_b32_e64 v106, v106, v113, s[52:53]
	v_cndmask_b32_e64 v105, v105, v113, s[50:51]
	v_cndmask_b32_e64 v104, v104, v113, s[48:49]
	v_cndmask_b32_e64 v103, v103, v113, s[46:47]
	v_cndmask_b32_e64 v102, v102, v113, s[44:45]
	v_cndmask_b32_e64 v101, v101, v113, s[42:43]
	v_cndmask_b32_e64 v100, v100, v113, s[40:41]
	v_cndmask_b32_e64 v99, v99, v113, s[38:39]
	v_cndmask_b32_e64 v98, v98, v113, s[36:37]
	v_cndmask_b32_e64 v97, v97, v113, s[34:35]
	v_cndmask_b32_e64 v95, v95, v228, s[30:31]
	v_cndmask_b32_e64 v94, v94, v228, s[28:29]
	v_cndmask_b32_e64 v93, v93, v228, s[26:27]
	v_cndmask_b32_e64 v92, v92, v228, s[24:25]
	v_cndmask_b32_e64 v91, v91, v228, s[22:23]
	v_cndmask_b32_e64 v90, v90, v228, s[20:21]
	v_cndmask_b32_e64 v89, v89, v228, s[18:19]
	v_cndmask_b32_e64 v88, v88, v228, s[16:17]
	v_cndmask_b32_e64 v87, v87, v228, s[14:15]
	v_cndmask_b32_e64 v86, v86, v228, s[12:13]
	v_cndmask_b32_e64 v85, v85, v228, s[10:11]
	v_cndmask_b32_e64 v84, v84, v228, s[8:9]
	v_cndmask_b32_e64 v83, v83, v228, s[6:7]
	v_cndmask_b32_e64 v82, v82, v228, s[4:5]
	v_cndmask_b32_e64 v81, v81, v228, s[0:1]
	v_cndmask_b32_e32 v80, v80, v228, vcc
.LBB0_327:
	s_waitcnt lgkmcnt(2)
	v_mfma_f32_32x32x16_bf16 v[48:63], v[182:185], v[174:177], v[48:63]
	v_add_f32_e32 v186, v255, v80
	v_exp_f32_e32 v186, v186
	ds_read_b64_tr_b16 v[154:155], v158 offset:40960
	ds_read_b64_tr_b16 v[156:157], v158 offset:43008
	v_add_f32_e32 v188, v186, v96
	s_waitcnt lgkmcnt(2)
	v_mfma_f32_32x32x16_bf16 v[48:63], v[178:181], v[162:165], v[48:63]
	v_add_f32_e32 v187, v255, v81
	v_exp_f32_e32 v187, v187
	ds_read_b64_tr_b16 v[182:183], v158 offset:45056
	ds_read_b64_tr_b16 v[184:185], v158 offset:47104
	v_add_f32_e32 v189, v187, v97
	v_add_f32_e32 v188, v189, v188
	v_cvt_pk_bf16_f32 v152, v96, v97
	v_cvt_pk_bf16_f32 v148, v186, v187
	s_waitcnt lgkmcnt(2)
	v_mfma_f32_32x32x16_bf16 v[48:63], v[154:157], v[170:173], v[48:63]
	v_add_f32_e32 v186, v255, v82
	v_exp_f32_e32 v186, v186
	v_add_u32_e32 v150, s3, v239
	ds_read_b64_tr_b16 v[158:159], v150 offset:32768
	ds_read_b64_tr_b16 v[160:161], v150 offset:34816
	v_add_f32_e32 v189, v186, v98
	v_add_f32_e32 v188, v189, v188
	s_waitcnt lgkmcnt(2)
	v_mfma_f32_32x32x16_bf16 v[48:63], v[182:185], v[166:169], v[48:63]
	v_add_f32_e32 v187, v255, v83
	v_exp_f32_e32 v187, v187
	ds_read_b64_tr_b16 v[80:81], v150 offset:36864
	ds_read_b64_tr_b16 v[82:83], v150 offset:38912
	v_add_f32_e32 v189, v187, v99
	v_add_f32_e32 v188, v189, v188
	v_cvt_pk_bf16_f32 v153, v98, v99
	v_cvt_pk_bf16_f32 v149, v186, v187
	s_waitcnt lgkmcnt(2)
	v_mfma_f32_32x32x16_bf16 v[32:47], v[158:161], v[174:177], v[32:47]
	v_add_f32_e32 v186, v255, v84
	v_exp_f32_e32 v186, v186
	ds_read_b64_tr_b16 v[96:97], v150 offset:40960
	ds_read_b64_tr_b16 v[98:99], v150 offset:43008
	v_add_f32_e32 v189, v186, v100
	v_add_f32_e32 v188, v189, v188
	s_waitcnt lgkmcnt(2)
	v_mfma_f32_32x32x16_bf16 v[32:47], v[80:83], v[162:165], v[32:47]
	v_add_f32_e32 v187, v255, v85
	v_exp_f32_e32 v187, v187
	ds_read_b64_tr_b16 v[156:157], v150 offset:45056
	ds_read_b64_tr_b16 v[158:159], v150 offset:47104
	v_add_f32_e32 v189, v187, v101
	v_add_f32_e32 v188, v189, v188
	v_cvt_pk_bf16_f32 v154, v100, v101
	v_cvt_pk_bf16_f32 v150, v186, v187
	s_waitcnt lgkmcnt(2)
	v_mfma_f32_32x32x16_bf16 v[32:47], v[96:99], v[170:173], v[32:47]
	v_add_f32_e32 v186, v255, v86
	v_exp_f32_e32 v186, v186
	v_add_u32_e32 v100, s3, v236
	ds_read_b64_tr_b16 v[80:81], v100 offset:32768
	ds_read_b64_tr_b16 v[82:83], v100 offset:34816
	v_add_f32_e32 v189, v186, v102
	v_add_f32_e32 v188, v189, v188
	s_waitcnt lgkmcnt(2)
	v_mfma_f32_32x32x16_bf16 v[32:47], v[156:159], v[166:169], v[32:47]
	v_add_f32_e32 v187, v255, v87
	v_exp_f32_e32 v187, v187
	ds_read_b64_tr_b16 v[84:85], v100 offset:36864
	ds_read_b64_tr_b16 v[86:87], v100 offset:38912
	v_add_f32_e32 v189, v187, v103
	v_add_f32_e32 v188, v189, v188
	v_cvt_pk_bf16_f32 v155, v102, v103
	v_cvt_pk_bf16_f32 v151, v186, v187
	s_waitcnt lgkmcnt(2)
	v_mfma_f32_32x32x16_bf16 v[16:31], v[80:83], v[174:177], v[16:31]
	v_add_f32_e32 v186, v255, v88
	v_exp_f32_e32 v186, v186
	ds_read_b64_tr_b16 v[96:97], v100 offset:40960
	ds_read_b64_tr_b16 v[98:99], v100 offset:43008
	v_add_f32_e32 v189, v186, v104
	v_add_f32_e32 v188, v189, v188
	s_waitcnt lgkmcnt(2)
	v_mfma_f32_32x32x16_bf16 v[16:31], v[84:87], v[162:165], v[16:31]
	v_add_f32_e32 v187, v255, v89
	v_exp_f32_e32 v187, v187
	ds_read_b64_tr_b16 v[80:81], v100 offset:45056
	ds_read_b64_tr_b16 v[82:83], v100 offset:47104
	v_add_f32_e32 v189, v187, v105
	v_add_f32_e32 v188, v189, v188
	v_cvt_pk_bf16_f32 v156, v104, v105
	v_cvt_pk_bf16_f32 v160, v186, v187
	s_waitcnt lgkmcnt(2)
	v_mfma_f32_32x32x16_bf16 v[16:31], v[96:99], v[170:173], v[16:31]
	v_add_f32_e32 v186, v255, v90
	v_exp_f32_e32 v186, v186
	v_add_u32_e32 v101, s3, v234
	ds_read_b64_tr_b16 v[84:85], v101 offset:32768
	ds_read_b64_tr_b16 v[86:87], v101 offset:34816
	v_add_f32_e32 v189, v186, v106
	v_add_f32_e32 v188, v189, v188
	s_waitcnt lgkmcnt(2)
	v_mfma_f32_32x32x16_bf16 v[16:31], v[80:83], v[166:169], v[16:31]
	v_add_f32_e32 v187, v255, v91
	v_exp_f32_e32 v187, v187
	ds_read_b64_tr_b16 v[88:89], v101 offset:36864
	ds_read_b64_tr_b16 v[90:91], v101 offset:38912
	v_add_f32_e32 v189, v187, v107
	v_add_f32_e32 v188, v189, v188
	v_cvt_pk_bf16_f32 v157, v106, v107
	v_cvt_pk_bf16_f32 v161, v186, v187
	s_waitcnt lgkmcnt(2)
	v_mfma_f32_32x32x16_bf16 v[0:15], v[84:87], v[174:177], v[0:15]
	v_add_f32_e32 v186, v255, v92
	v_exp_f32_e32 v186, v186
	ds_read_b64_tr_b16 v[80:81], v101 offset:40960
	ds_read_b64_tr_b16 v[82:83], v101 offset:43008
	v_add_f32_e32 v189, v186, v108
	v_add_f32_e32 v188, v189, v188
	s_waitcnt lgkmcnt(2)
	v_mfma_f32_32x32x16_bf16 v[0:15], v[88:91], v[162:165], v[0:15]
	v_add_f32_e32 v187, v255, v93
	v_exp_f32_e32 v187, v187
	ds_read_b64_tr_b16 v[84:85], v101 offset:45056
	ds_read_b64_tr_b16 v[86:87], v101 offset:47104
	v_add_f32_e32 v189, v187, v109
	v_add_f32_e32 v188, v189, v188
	v_cvt_pk_bf16_f32 v164, v108, v109
	v_cvt_pk_bf16_f32 v162, v186, v187
	s_waitcnt lgkmcnt(2)
	v_mfma_f32_32x32x16_bf16 v[0:15], v[80:83], v[170:173], v[0:15]
	v_add_f32_e32 v186, v255, v94
	v_exp_f32_e32 v186, v186
	s_nop 0
	v_add_f32_e32 v189, v186, v110
	v_add_f32_e32 v188, v189, v188
	s_waitcnt lgkmcnt(0)
	v_mfma_f32_32x32x16_bf16 v[0:15], v[84:87], v[166:169], v[0:15]
	v_add_f32_e32 v187, v255, v95
	v_exp_f32_e32 v187, v187
	s_nop 0
	v_add_f32_e32 v189, v187, v111
	v_add_f32_e32 v188, v189, v188
	v_cvt_pk_bf16_f32 v165, v110, v111
	v_cvt_pk_bf16_f32 v169, v186, v187
	s_add_i32 s0, s72, 1
	s_add_i32 s79, s79, 0x8000
	s_add_i32 s97, s97, 64
	s_add_i32 s1, s72, 2
	v_add_f32_e32 v229, v229, v188
	s_cmp_ge_i32 s1, s82
	v_subrev_u32_e32 v240, 64, v240
	s_cbranch_scc1 .LBB0_332
	s_mov_b32 s72, s0
	s_cmp_ge_i32 s72, s73
	s_mov_b64 s[0:1], -1
	s_cbranch_scc1 .LBB0_320
	s_branch .LBB0_321
